# GEMM epilogues: static s_setprio 1 for waves 0-3 during each epilogue (K-loop flips reset it), on v53
# baseline (speedup 1.0000x reference)
; __device__ __forceinline__ int lane_id_asm() { int l; asm volatile("v_mbcnt_lo_u32_b32 %0, -1, 0\n\tv_mbcnt_hi_u32_b32 %0, -1, %0" : "=v"(l)); return l; }
; #define PG8_BAR __builtin_amdgcn_s_barrier()
; template <class Epi>
; __device__ __forceinline__ void gemm_phase(LAS unsigned char* lds, const Gemm g, const StaticOrder& S, const Epi& E, const int wid) {
;     ...
;         if (wr == 0) PG8_BAR;
;         E(acc, cur, wid);
;     __device__ __forceinline__ void operator()(const Acc& acc, const pg8::Unit& u, int wid) const {
;         const int lane_ = lane_id_asm(), wr = wid >> 2, wc = wid & 3, fr = lane_ & 15, fq = lane_ >> 4;
;         const int row0 = u.pm * 256 + wr * 64 + fr, colL = wc * 32 + 8 * fq, pn = u.pn;
.LBB0_194:
	s_cmpk_lt_u32 s3, 0x100
	s_cbranch_scc0 .Lepi_np_0
	s_setprio 1

; #define LAS __attribute__((address_space(3)))
; __device__ __forceinline__ void ret_mfma(const Params& P, LAS unsigned char* lds, int wave) {
;     ...
;     for (int unit = blockIdx.x; unit < 256; unit += gridDim.x) {
;         const int xcd_ = unit & 7, idx_ = unit >> 3, bh = xcd_ * 4 + (idx_ >> 3), slice = idx_ & 7, b = bh >> 2, hh = bh & 3;
;         const float gam = 1.f - exp2f(-5.f - (float)hh), lg = log2f(gam), g64 = exp2f(lg * 64.f);
;         for (int i = t; i < 33792 / 16; i += NTHREADS) *(LAS u32x4*)(lds + ST_OFF + i * 16) = (u32x4){0u, 0u, 0u, 0u};
;         f32x16 st[2];
; #pragma unroll
;         for (int a = 0; a < 2; ++a)
; #pragma unroll
;             for (int i = 0; i < 16; ++i) st[a][i] = 0.f;
;         const size_t rb = (size_t)b * SEQ;
;         float dec[16];
;         { const int mblk = (wave & 3) >> 1, nblk = wave & 1, n = nblk * 32 + q32;
; #pragma unroll
;           for (int i = 0; i < 16; ++i) { const int mm = mblk * 32 + 8 * (i >> 2) + 4 * hf + (i & 3); const int dist = n > mm ? n - mm : mm - n;
;               dec[i] = wave < 4 ? __builtin_amdgcn_exp2f(lg * (float)(dist - (63 - mm))) : __builtin_amdgcn_exp2f(lg * (float)(n + 1)); } }
;         u32x4 pq[4], pkk[4], pvv;
;         const int vr = t >> 3, vc = t & 7;
; #pragma unroll
;         for (int i = 0; i < 4; ++i) { const int id = t + 512 * i, r = id >> 5, ch = id & 31;
;             pq[i] = *(const u32x4*)(QK + (rb + r) * 2048 + hh * 256 + ch * 8); pkk[i] = *(const u32x4*)(QK + (rb + r) * 2048 + 1024 + hh * 256 + ch * 8); }
;         pvv = *(const u32x4*)(V + (rb + vr) * 2048 + hh * 512 + slice * 64 + vc * 8);
.LBB0_246:
	s_or_b64 exec, exec, s[50:51]
	s_add_u32 s60, s54, 0x1f000000
	s_addc_u32 s61, s55, 0
	s_cmpk_gt_i32 s2, 0xff
	s_waitcnt lgkmcnt(0)
	s_barrier
	v_mbcnt_lo_u32_b32 v0, -1, 0
	v_mbcnt_hi_u32_b32 v0, -1, v0
	s_cbranch_scc1 .LBB0_270
	v_ashrrev_i32_e32 v3, 5, v0
	v_and_b32_e32 v8, 31, v0
	v_readlane_b32 s4, v254, 4
	s_cmpk_lt_u32 s3, 0x100
	v_lshlrev_b32_e32 v5, 3, v3
	v_lshrrev_b32_e32 v2, 2, v0
	v_and_or_b32 v84, s4, 32, v8
	s_cselect_b64 s[4:5], -1, 0
	s_cmpk_gt_u32 s3, 0xff
	v_add_u32_e32 v1, s64, v0
	v_and_or_b32 v6, v2, 3, v5
	v_lshlrev_b32_e32 v2, 2, v0
	v_and_b32_e32 v4, 16, v0
	s_cselect_b64 s[10:11], -1, 0
	s_lshl_b32 s6, s33, 4
	v_and_or_b32 v2, v2, 12, v4
	s_and_b32 s6, s6, 32
	v_lshlrev_b32_e32 v86, 2, v3
	v_ashrrev_i32_e32 v88, 3, v1
	s_movk_i32 s9, 0xc0
	v_lshlrev_b32_e32 v7, 1, v2
	v_add_u32_e32 v9, s6, v86
	v_mul_lo_u32 v13, v88, s9
	s_add_i32 s6, 0, 0x10800
	v_add_u32_e32 v13, s6, v13
	v_add_u32_e32 v148, s6, v7
	s_add_i32 s6, s64, 0
	s_add_i32 s16, 0, 0x16800
	s_add_i32 s7, 0, 0x1ec00
	v_add_u32_e32 v7, s6, v7
	s_add_i32 s6, s16, s64
	v_lshlrev_b32_e32 v149, 4, v3
	v_mul_u32_u24_e32 v15, 0x210, v84
	v_lshl_add_u32 v14, v8, 1, s6
	v_add3_u32 v150, 0, v15, v149
	s_movk_i32 s6, 0x90
	v_mov_b32_e32 v15, s7
	v_add_u32_e32 v2, 1, v84
	v_mad_u32_u24 v151, v84, s6, v15
	s_add_i32 s6, s33, -4
	v_cvt_f32_ubyte0_e32 v85, v2
	v_and_b32_e32 v10, 7, v0
	v_lshlrev_b32_e32 v2, 3, v0
	v_lshlrev_b32_e32 v11, 4, v0
	s_lshr_b32 s14, s6, 1
	v_cmp_lt_u32_e64 s[6:7], 31, v0
	v_sub_u32_e32 v0, v84, v9
	v_sub_u32_e32 v16, 0, v0
	v_max_i32_e32 v16, v0, v16
	s_movk_i32 s21, 0xffc1
	v_add3_u32 v16, v9, v16, s21
	v_cvt_f32_i32_e32 v152, v16
	v_xad_u32 v16, v9, -1, v84
	v_sub_u32_e32 v17, 0, v16
	v_max_i32_e32 v16, v16, v17
	s_movk_i32 s21, 0xffc2
	v_add3_u32 v16, v9, v16, s21
	v_cvt_f32_i32_e32 v153, v16
	v_add_u32_e32 v16, -2, v0
	v_sub_u32_e32 v17, 2, v0
	v_max_i32_e32 v16, v16, v17
	s_movk_i32 s21, 0xffc3
	v_add3_u32 v16, v9, v16, s21
	v_cvt_f32_i32_e32 v154, v16
	v_add_u32_e32 v16, -3, v0
	v_sub_u32_e32 v17, 3, v0
	v_max_i32_e32 v16, v16, v17
	s_movk_i32 s21, 0xffc4
	v_add3_u32 v16, v9, v16, s21
	v_cvt_f32_i32_e32 v155, v16
	v_add_u32_e32 v16, -8, v0
	v_sub_u32_e32 v17, 8, v0
	v_max_i32_e32 v16, v16, v17
	s_movk_i32 s21, 0xffc9
	v_add3_u32 v16, v9, v16, s21
	v_cvt_f32_i32_e32 v156, v16
	v_add_u32_e32 v16, -9, v0
	v_sub_u32_e32 v17, 9, v0
	v_max_i32_e32 v16, v16, v17
	s_movk_i32 s21, 0xffca
	v_add3_u32 v16, v9, v16, s21
	v_cvt_f32_i32_e32 v157, v16
	v_add_u32_e32 v16, -10, v0
	v_sub_u32_e32 v17, 10, v0
	v_max_i32_e32 v16, v16, v17
	s_movk_i32 s21, 0xffcb
	v_add3_u32 v16, v9, v16, s21
	v_cvt_f32_i32_e32 v158, v16
	v_add_u32_e32 v16, -11, v0
	v_sub_u32_e32 v17, 11, v0
	v_max_i32_e32 v16, v16, v17
	s_movk_i32 s21, 0xffcc
	v_add3_u32 v16, v9, v16, s21
	v_cvt_f32_i32_e32 v159, v16
	v_add_u32_e32 v16, -16, v0
	v_sub_u32_e32 v17, 16, v0
	v_max_i32_e32 v16, v16, v17
	s_movk_i32 s21, 0xffd1
	v_add3_u32 v16, v9, v16, s21
	v_cvt_f32_i32_e32 v160, v16
	v_subrev_u32_e32 v16, 17, v0
	v_sub_u32_e32 v17, 17, v0
	v_max_i32_e32 v16, v16, v17
	s_movk_i32 s21, 0xffd2
	v_add3_u32 v16, v9, v16, s21
	v_cvt_f32_i32_e32 v161, v16
	v_subrev_u32_e32 v16, 18, v0
	v_sub_u32_e32 v17, 18, v0
	v_max_i32_e32 v16, v16, v17
	s_movk_i32 s21, 0xffd3
	v_add3_u32 v16, v9, v16, s21
	v_cvt_f32_i32_e32 v162, v16
	v_subrev_u32_e32 v16, 19, v0
	v_sub_u32_e32 v17, 19, v0
	v_max_i32_e32 v16, v16, v17
	s_movk_i32 s21, 0xffd4
	v_add3_u32 v16, v9, v16, s21
	v_cvt_f32_i32_e32 v163, v16
	v_subrev_u32_e32 v16, 24, v0
	v_sub_u32_e32 v17, 24, v0
	v_max_i32_e32 v16, v16, v17
	s_movk_i32 s21, 0xffd9
	v_add3_u32 v16, v9, v16, s21
	v_cvt_f32_i32_e32 v164, v16
	v_subrev_u32_e32 v16, 25, v0
	v_sub_u32_e32 v17, 25, v0
	v_max_i32_e32 v16, v16, v17
	s_movk_i32 s21, 0xffda
	v_add3_u32 v16, v9, v16, s21
	v_cvt_f32_i32_e32 v165, v16
	v_subrev_u32_e32 v16, 26, v0
	v_sub_u32_e32 v17, 26, v0
	v_max_i32_e32 v16, v16, v17
	s_movk_i32 s21, 0xffdb
	v_add3_u32 v16, v9, v16, s21
	v_cvt_f32_i32_e32 v166, v16
	v_subrev_u32_e32 v16, 27, v0
	v_sub_u32_e32 v0, 27, v0
	v_max_i32_e32 v0, v16, v0
	s_movk_i32 s21, 0xffdc
	v_add3_u32 v0, v9, v0, s21
	s_movk_i32 s8, 0x840
	s_lshr_b32 s18, s3, 7
	v_cvt_f32_i32_e32 v167, v0
	v_add_u32_e32 v0, 0x200, v1
	v_cmp_gt_i32_e64 s[0:1], s8, v1
	v_ashrrev_i32_e32 v94, 5, v0
	v_add_u32_e32 v0, 0x400, v1
	v_mul_lo_u32 v3, v3, s8
	s_mul_i32 s8, s18, 0x4200
	s_movk_i32 s17, 0x210
	v_ashrrev_i32_e32 v92, 5, v1
	v_ashrrev_i32_e32 v96, 5, v0
	v_add_u32_e32 v0, 0x600, v1
	v_add_u32_e32 v169, 0xfffffe00, v1
	v_mov_b32_e32 v1, s8
	v_and_b32_e32 v2, 0xf8, v2
	v_and_b32_e32 v12, 0x1f0, v11
	v_ashrrev_i32_e32 v98, 5, v0
	v_mad_u32_u24 v1, v8, s17, v1
	s_mov_b32 s15, 0
	v_mov_b32_e32 v91, 0
	v_lshlrev_b32_e32 v4, 3, v10
	v_add_u32_e32 v12, 0, v12
	v_lshlrev_b32_e32 v10, 4, v10
	s_lshl_b32 s19, s18, 6
	v_add_u32_e32 v5, v151, v5
	v_lshl_add_u32 v15, s14, 6, v148
	s_lshl_b32 s20, s14, 5
	v_mul_lo_u32 v0, v92, s17
	v_mul_lo_u32 v9, v94, s17
	v_mul_lo_u32 v16, v96, s17
	v_mul_lo_u32 v17, v98, s17
	v_mul_lo_u32 v168, v6, s9
	v_mul_lo_u32 v6, v6, s17
	v_lshlrev_b32_e32 v90, 1, v2
	s_add_i32 s16, s16, s68
	v_add3_u32 v1, v1, v149, 0
	v_ashrrev_i32_e32 v89, 31, v88
	v_ashrrev_i32_e32 v87, 31, v86
	v_ashrrev_i32_e32 v93, 31, v92
	v_ashrrev_i32_e32 v95, 31, v94
	v_ashrrev_i32_e32 v97, 31, v96
	v_ashrrev_i32_e32 v99, 31, v98
	v_lshl_add_u64 v[100:101], s[44:45], 0, v[90:91]
	v_add_u32_e32 v170, s16, v11
	v_add_u32_e32 v171, 0xe400, v1
	v_add_u32_e32 v172, 0x8400, v1
	s_movk_i32 s24, 0x63f
	s_mov_b32 s25, 0xc2fc0000
	s_mov_b32 s26, 0x800000
	v_lshlrev_b32_e32 v90, 1, v2
	v_lshlrev_b32_e32 v102, 1, v4
	s_lshl_b64 s[16:17], s[14:15], 2
	s_lshl_b32 s27, s20, 1
	v_add_u32_e32 v173, v12, v0
	v_add_u32_e32 v174, v12, v9
	v_add_u32_e32 v175, v12, v16
	v_add_u32_e32 v176, v12, v17
	v_add_u32_e32 v177, v13, v10
	v_add_u32_e32 v178, s19, v5
	v_add_u32_e32 v179, v7, v6
	v_add_u32_e32 v180, v14, v3
	v_add_u32_e32 v181, v15, v168
	v_mov_b32_e32 v186, v91
	v_mov_b32_e32 v187, v91
	v_mov_b32_e32 v188, v91
	v_mov_b32_e32 v189, v91
	v_mov_b32_e32 v182, 0x42800000
	v_mov_b32_e32 v183, 0x42000000
	v_mbcnt_hi_u32_b32 v184, -1, v244
	v_and_b32_e32 v142, 32, v184
	v_mov_b32_e32 v143, 0
	v_lshrrev_b32_e32 v142, 2, v142
	v_and_b32_e32 v242, 31, v184
	v_mul_u32_u24_e32 v242, 0x210, v242
	v_lshrrev_b32_e32 v103, 5, v184
	v_lshl_add_u32 v242, v103, 3, v242
	v_add_u32_e32 v242, s64, v242
	v_add_u32_e32 v242, 0x16800, v242
	s_mov_b32 s28, s2
	s_setprio 0
	s_branch .LBB0_249
